# P3/P5 panel exchange: only wave 0 polls the counter, the other seven waves wait at the barrier behind it
# speedup vs baseline: 1.0063x; 1.0011x over previous
.LBB0_389:
	s_or_b64 exec, exec, s[10:11]
	s_cmp_gt_u32 s47, 63
	s_cbranch_scc1 .LBB0_393
	v_readfirstlane_b32 s100, v228
	s_lshr_b32 s100, s100, 6
	s_cmp_lg_u32 s100, 0
	s_cbranch_scc1 .LBB0_393
	s_lshl_b32 s10, s36, 6
	s_ashr_i32 s11, s10, 31
	s_lshl_b64 s[10:11], s[10:11], 2
	s_add_u32 s10, s33, s10
	s_addc_u32 s11, s41, s11
	s_mov_b32 s26, 0

.LBB0_623:
	s_or_b64 exec, exec, s[8:9]
	s_cmp_gt_u32 s36, 63
	s_cbranch_scc1 .LBB0_627
	v_readfirstlane_b32 s100, v228
	s_lshr_b32 s100, s100, 6
	s_cmp_lg_u32 s100, 0
	s_cbranch_scc1 .LBB0_627
	s_lshl_b32 s8, s6, 6
	s_ashr_i32 s9, s8, 31
	s_lshl_b64 s[8:9], s[8:9], 2
	s_add_u32 s8, s27, s8
	s_addc_u32 s9, s28, s9
	s_mov_b32 s3, 0
